# K-loops: redundant lgkmcnt(0) after the phase barrier dropped, priority raise moved before the barrier (first MFMA directly after release); on v38
# speedup vs baseline: 1.0257x; 1.0257x over previous
; #define PG8_STAGE(bufoff, gbase, voff) do { _Pragma("unroll") for (int _i = 0; _i < 2; ++_i) \
;         __builtin_amdgcn_global_load_lds((const unsigned*)((const char*)(gbase) + (voff)[_i]), (PG8_LAS unsigned*)(lds + (bufoff) + ldsw + _i * 8192), 16, 0, 0); } while (0)
; #define PG8_LDA(dst, b, h) do { _Pragma("unroll") for (int m = 0; m < 4; ++m) _Pragma("unroll") for (int k = 0; k < 2; ++k) dst[m][k] = *(const PG8_LAS bf16x8*)(lds + PG8_SA(b, h) + aoff + m * 2048 + k * 1024); } while (0)
; #define PG8_MMA(ai, bj, At, Bt) do { __builtin_amdgcn_s_setprio(1); _Pragma("unroll") for (int m = 0; m < 4; ++m) _Pragma("unroll") for (int n = 0; n < 2; ++n) _Pragma("unroll") for (int k = 0; k < 2; ++k) \
;         acc[ai][bj][m][n] = __builtin_amdgcn_mfma_f32_16x16x32_bf16(Bt[n][k], At[m][k], acc[ai][bj][m][n], 0, 0, 0); __builtin_amdgcn_s_setprio(0); } while (0)
; #define PG8_WAIT_V(n) asm volatile("s_waitcnt vmcnt(" #n ")" ::: "memory")
; #define PG8_WAIT_L(n) asm volatile("s_waitcnt lgkmcnt(" #n ")" ::: "memory")
; #define PG8_BAR __builtin_amdgcn_s_barrier()
; #define PG8_SCHED __builtin_amdgcn_sched_barrier(0)
; template <class Epi, class Sched, bool ALIGN_EPI = false, bool SP2 = false>
; __device__ __forceinline__ void gemm_phase(PG8_LAS unsigned char* lds, const Gemm g, const Sched& S, const Epi& E, const int tid) {
;     ...
;             PG8_WAIT_V(8); PG8_WAIT_L(0); PG8_BAR; PG8_MMA(0, 0, At, B0); PG8_MMA(0, 1, At, B1); PG8_BAR; PG8_SCHED;
;             PG8_LDA(At, 0, 1); PG8_STAGE(PG8_SB(0, 0), b2, voffB); PG8_STAGE(PG8_SB(0, 1), b2 + hstepB, voffB); PG8_STAGE(PG8_SA(0, 0), a2, voffA);
;             PG8_WAIT_V(8); PG8_WAIT_L(0); PG8_BAR; PG8_MMA(1, 0, At, B0); PG8_MMA(1, 1, At, B1); PG8_BAR; PG8_SCHED;
.Lkw_up_0:
	s_waitcnt lgkmcnt(0)
	s_setprio 1
	s_barrier
	v_mfma_f32_16x16x32_bf16 v[124:127], v[148:151], v[208:211], v[124:127]
	v_mfma_f32_16x16x32_bf16 v[120:123], v[162:165], v[208:211], v[120:123]
	v_mfma_f32_16x16x32_bf16 v[108:111], v[148:151], v[216:219], v[108:111]
	v_mfma_f32_16x16x32_bf16 v[104:107], v[162:165], v[216:219], v[104:107]
	v_mfma_f32_16x16x32_bf16 v[92:95], v[148:151], v[224:227], v[92:95]
	v_mfma_f32_16x16x32_bf16 v[88:91], v[162:165], v[224:227], v[88:91]
	v_mfma_f32_16x16x32_bf16 v[76:79], v[148:151], v[232:235], v[76:79]
	v_mfma_f32_16x16x32_bf16 v[72:75], v[162:165], v[232:235], v[72:75]
	v_mfma_f32_16x16x32_bf16 v[124:127], v[158:161], v[212:215], v[124:127]
	v_mfma_f32_16x16x32_bf16 v[120:123], v[188:191], v[212:215], v[120:123]
	v_mfma_f32_16x16x32_bf16 v[108:111], v[158:161], v[220:223], v[108:111]
	v_mfma_f32_16x16x32_bf16 v[104:107], v[188:191], v[220:223], v[104:107]
	v_mfma_f32_16x16x32_bf16 v[92:95], v[158:161], v[228:231], v[92:95]
	v_mfma_f32_16x16x32_bf16 v[88:91], v[188:191], v[228:231], v[88:91]
	v_mfma_f32_16x16x32_bf16 v[76:79], v[158:161], v[236:239], v[76:79]
	v_mfma_f32_16x16x32_bf16 v[72:75], v[188:191], v[236:239], v[72:75]
	s_setprio 0
	s_setprio 1
	v_mfma_f32_16x16x32_bf16 v[116:119], v[192:195], v[208:211], v[116:119]
	v_mfma_f32_16x16x32_bf16 v[112:115], v[200:203], v[208:211], v[112:115]
	v_mfma_f32_16x16x32_bf16 v[100:103], v[192:195], v[216:219], v[100:103]
	v_mfma_f32_16x16x32_bf16 v[96:99], v[200:203], v[216:219], v[96:99]
	v_mfma_f32_16x16x32_bf16 v[84:87], v[192:195], v[224:227], v[84:87]
	v_mfma_f32_16x16x32_bf16 v[80:83], v[200:203], v[224:227], v[80:83]
	v_mfma_f32_16x16x32_bf16 v[68:71], v[192:195], v[232:235], v[68:71]
	v_mfma_f32_16x16x32_bf16 v[64:67], v[200:203], v[232:235], v[64:67]
	v_mfma_f32_16x16x32_bf16 v[116:119], v[196:199], v[212:215], v[116:119]
	v_mfma_f32_16x16x32_bf16 v[112:115], v[204:207], v[212:215], v[112:115]
	v_mfma_f32_16x16x32_bf16 v[100:103], v[196:199], v[220:223], v[100:103]
	v_mfma_f32_16x16x32_bf16 v[96:99], v[204:207], v[220:223], v[96:99]
	v_mfma_f32_16x16x32_bf16 v[84:87], v[196:199], v[228:231], v[84:87]
	v_mfma_f32_16x16x32_bf16 v[80:83], v[204:207], v[228:231], v[80:83]
	v_mfma_f32_16x16x32_bf16 v[68:71], v[196:199], v[236:239], v[68:71]
	v_mfma_f32_16x16x32_bf16 v[64:67], v[204:207], v[236:239], v[64:67]
	s_setprio 0
	s_barrier
	s_add_i32 s36, s36, s68
	v_lshl_add_u64 v[166:167], s[18:19], 0, v[140:141]
	s_mov_b32 m0, s36
	ds_read_b128 v[208:211], v157 offset:16384
	ds_read_b128 v[212:215], v157 offset:17408
	ds_read_b128 v[216:219], v157 offset:18432
	ds_read_b128 v[220:223], v157 offset:19456
	ds_read_b128 v[224:227], v157 offset:20480
	ds_read_b128 v[228:231], v157 offset:21504
	ds_read_b128 v[232:235], v157 offset:22528
	ds_read_b128 v[236:239], v157 offset:23552
	global_load_lds_dwordx4 v[166:167], off
	s_add_i32 m0, s36, 0x2000
	s_add_u32 s36, s18, 0x40000
	v_lshl_add_u64 v[240:241], s[18:19], 0, v[136:137]
	s_addc_u32 s37, s19, 0
	s_add_i32 s38, s38, s68
	global_load_lds_dwordx4 v[240:241], off
	v_lshl_add_u64 v[242:243], s[36:37], 0, v[140:141]
	s_mov_b32 m0, s38
	v_lshl_add_u64 v[244:245], s[22:23], 0, v[138:139]
	global_load_lds_dwordx4 v[242:243], off
	v_lshl_add_u64 v[242:243], s[36:37], 0, v[136:137]
	s_add_i32 m0, s38, 0x2000
	s_nop 0
	global_load_lds_dwordx4 v[242:243], off
	v_lshl_add_u64 v[242:243], s[22:23], 0, v[142:143]
	s_mov_b32 m0, s69
	s_nop 0
	global_load_lds_dwordx4 v[242:243], off
	s_mov_b32 m0, s70
	s_nop 0
	global_load_lds_dwordx4 v[244:245], off
	s_cmp_eq_u32 s99, 1
	s_cbranch_scc1 .Lkw_up_1
	s_waitcnt vmcnt(8)
.Lkw_up_1:
	s_waitcnt lgkmcnt(0)
	s_setprio 1
	s_barrier
	v_mfma_f32_16x16x32_bf16 v[60:63], v[148:151], v[208:211], v[60:63]
	v_mfma_f32_16x16x32_bf16 v[56:59], v[162:165], v[208:211], v[56:59]
	v_mfma_f32_16x16x32_bf16 v[44:47], v[148:151], v[216:219], v[44:47]
	v_mfma_f32_16x16x32_bf16 v[40:43], v[162:165], v[216:219], v[40:43]
	v_mfma_f32_16x16x32_bf16 v[28:31], v[148:151], v[224:227], v[28:31]
	v_mfma_f32_16x16x32_bf16 v[24:27], v[162:165], v[224:227], v[24:27]
	v_mfma_f32_16x16x32_bf16 v[12:15], v[148:151], v[232:235], v[12:15]
	v_mfma_f32_16x16x32_bf16 v[8:11], v[162:165], v[232:235], v[8:11]
	v_mfma_f32_16x16x32_bf16 v[60:63], v[158:161], v[212:215], v[60:63]
	v_mfma_f32_16x16x32_bf16 v[56:59], v[188:191], v[212:215], v[56:59]
	v_mfma_f32_16x16x32_bf16 v[44:47], v[158:161], v[220:223], v[44:47]
	v_mfma_f32_16x16x32_bf16 v[40:43], v[188:191], v[220:223], v[40:43]
	v_mfma_f32_16x16x32_bf16 v[28:31], v[158:161], v[228:231], v[28:31]
	v_mfma_f32_16x16x32_bf16 v[24:27], v[188:191], v[228:231], v[24:27]
	v_mfma_f32_16x16x32_bf16 v[12:15], v[158:161], v[236:239], v[12:15]
	v_mfma_f32_16x16x32_bf16 v[8:11], v[188:191], v[236:239], v[8:11]
	s_setprio 0
	s_setprio 1
	v_mfma_f32_16x16x32_bf16 v[52:55], v[192:195], v[208:211], v[52:55]
	v_mfma_f32_16x16x32_bf16 v[48:51], v[200:203], v[208:211], v[48:51]
	v_mfma_f32_16x16x32_bf16 v[36:39], v[192:195], v[216:219], v[36:39]
	v_mfma_f32_16x16x32_bf16 v[32:35], v[200:203], v[216:219], v[32:35]
	v_mfma_f32_16x16x32_bf16 v[20:23], v[192:195], v[224:227], v[20:23]
	v_mfma_f32_16x16x32_bf16 v[16:19], v[200:203], v[224:227], v[16:19]
	v_mfma_f32_16x16x32_bf16 v[4:7], v[192:195], v[232:235], v[4:7]
	v_mfma_f32_16x16x32_bf16 v[0:3], v[200:203], v[232:235], v[0:3]
	v_mfma_f32_16x16x32_bf16 v[52:55], v[196:199], v[212:215], v[52:55]
	v_mfma_f32_16x16x32_bf16 v[48:51], v[204:207], v[212:215], v[48:51]
	v_mfma_f32_16x16x32_bf16 v[36:39], v[196:199], v[220:223], v[36:39]
	v_mfma_f32_16x16x32_bf16 v[32:35], v[204:207], v[220:223], v[32:35]
	v_mfma_f32_16x16x32_bf16 v[20:23], v[196:199], v[228:231], v[20:23]
	v_mfma_f32_16x16x32_bf16 v[16:19], v[204:207], v[228:231], v[16:19]
	v_mfma_f32_16x16x32_bf16 v[4:7], v[196:199], v[236:239], v[4:7]
	v_mfma_f32_16x16x32_bf16 v[0:3], v[204:207], v[236:239], v[0:3]
	s_setprio 0
	s_barrier
; #define PG8_STAGE(bufoff, gbase, voff) do { _Pragma("unroll") for (int _i = 0; _i < 2; ++_i) \
;         __builtin_amdgcn_global_load_lds((const unsigned*)((const char*)(gbase) + (voff)[_i]), (PG8_LAS unsigned*)(lds + (bufoff) + ldsw + _i * 8192), 16, 0, 0); } while (0)
; #define PG8_LDA(dst, b, h) do { _Pragma("unroll") for (int m = 0; m < 4; ++m) _Pragma("unroll") for (int k = 0; k < 2; ++k) dst[m][k] = *(const PG8_LAS bf16x8*)(lds + PG8_SA(b, h) + aoff + m * 2048 + k * 1024); } while (0)
; #define PG8_LDB(dst, b, h) do { _Pragma("unroll") for (int n = 0; n < 2; ++n) _Pragma("unroll") for (int k = 0; k < 2; ++k) dst[n][k] = *(const PG8_LAS bf16x8*)(lds + PG8_SB(b, h) + boff + n * 2048 + k * 1024); } while (0)
; #define PG8_MMA(ai, bj, At, Bt) do { __builtin_amdgcn_s_setprio(1); _Pragma("unroll") for (int m = 0; m < 4; ++m) _Pragma("unroll") for (int n = 0; n < 2; ++n) _Pragma("unroll") for (int k = 0; k < 2; ++k) \
;         acc[ai][bj][m][n] = __builtin_amdgcn_mfma_f32_16x16x32_bf16(Bt[n][k], At[m][k], acc[ai][bj][m][n], 0, 0, 0); __builtin_amdgcn_s_setprio(0); } while (0)
; #define PG8_WAIT_V(n) asm volatile("s_waitcnt vmcnt(" #n ")" ::: "memory")
; #define PG8_WAIT_L(n) asm volatile("s_waitcnt lgkmcnt(" #n ")" ::: "memory")
; #define PG8_BAR __builtin_amdgcn_s_barrier()
; #define PG8_SCHED __builtin_amdgcn_sched_barrier(0)
; template <class Epi, class Sched, bool ALIGN_EPI = false, bool SP2 = false>
; __device__ __forceinline__ void gemm_phase(PG8_LAS unsigned char* lds, const Gemm g, const Sched& S, const Epi& E, const int tid) {
;     ...
;             PG8_LDB(B0, 1, 0); PG8_LDB(B1, 1, 1); PG8_SCHED; PG8_LDA(At, 1, 0); PG8_STAGE(PG8_SA(0, 1), a2 + hstepA, voffA);
;             PG8_WAIT_V(8); PG8_WAIT_L(0); PG8_BAR; PG8_MMA(0, 0, At, B0); PG8_MMA(0, 1, At, B1); PG8_BAR; PG8_SCHED;
	s_add_i32 s36, 0, 0x18000
	v_add_u32_e32 v128, s36, v155
	s_add_i32 s37, 0, 0x1c000
	ds_read_b128 v[148:151], v128
	ds_read_b128 v[158:161], v128 offset:1024
	ds_read_b128 v[162:165], v128 offset:2048
	ds_read_b128 v[188:191], v128 offset:3072
	v_add_u32_e32 v128, s37, v155
	ds_read_b128 v[192:195], v128
	ds_read_b128 v[196:199], v128 offset:1024
	ds_read_b128 v[200:203], v128 offset:2048
	ds_read_b128 v[204:207], v128 offset:3072
	s_add_u32 s22, s22, 0x80000
	s_addc_u32 s23, s23, 0
	s_mov_b32 m0, s71
	v_lshl_add_u64 v[246:247], s[22:23], 0, v[142:143]
	ds_read_b128 v[208:211], v157 offset:32768
	ds_read_b128 v[212:215], v157 offset:33792
	ds_read_b128 v[216:219], v157 offset:34816
	ds_read_b128 v[220:223], v157 offset:35840
	ds_read_b128 v[224:227], v157 offset:36864
	ds_read_b128 v[228:231], v157 offset:37888
	ds_read_b128 v[232:235], v157 offset:38912
	ds_read_b128 v[236:239], v157 offset:39936
	global_load_lds_dwordx4 v[246:247], off
	v_lshl_add_u64 v[246:247], s[22:23], 0, v[138:139]
	s_mov_b32 m0, s74
	s_nop 0
	global_load_lds_dwordx4 v[246:247], off
	s_waitcnt vmcnt(8)
	s_waitcnt lgkmcnt(0)
	s_setprio 1
	s_barrier
	v_mfma_f32_16x16x32_bf16 v[124:127], v[148:151], v[208:211], v[124:127]
	v_mfma_f32_16x16x32_bf16 v[120:123], v[162:165], v[208:211], v[120:123]
	v_mfma_f32_16x16x32_bf16 v[108:111], v[148:151], v[216:219], v[108:111]
	v_mfma_f32_16x16x32_bf16 v[104:107], v[162:165], v[216:219], v[104:107]
	v_mfma_f32_16x16x32_bf16 v[92:95], v[148:151], v[224:227], v[92:95]
	v_mfma_f32_16x16x32_bf16 v[88:91], v[162:165], v[224:227], v[88:91]
	v_mfma_f32_16x16x32_bf16 v[76:79], v[148:151], v[232:235], v[76:79]
	v_mfma_f32_16x16x32_bf16 v[72:75], v[162:165], v[232:235], v[72:75]
	v_mfma_f32_16x16x32_bf16 v[124:127], v[158:161], v[212:215], v[124:127]
	v_mfma_f32_16x16x32_bf16 v[120:123], v[188:191], v[212:215], v[120:123]
	v_mfma_f32_16x16x32_bf16 v[108:111], v[158:161], v[220:223], v[108:111]
	v_mfma_f32_16x16x32_bf16 v[104:107], v[188:191], v[220:223], v[104:107]
	v_mfma_f32_16x16x32_bf16 v[92:95], v[158:161], v[228:231], v[92:95]
	v_mfma_f32_16x16x32_bf16 v[88:91], v[188:191], v[228:231], v[88:91]
	v_mfma_f32_16x16x32_bf16 v[76:79], v[158:161], v[236:239], v[76:79]
	v_mfma_f32_16x16x32_bf16 v[72:75], v[188:191], v[236:239], v[72:75]
	s_setprio 0
	s_setprio 1
	v_mfma_f32_16x16x32_bf16 v[116:119], v[192:195], v[208:211], v[116:119]
	v_mfma_f32_16x16x32_bf16 v[112:115], v[200:203], v[208:211], v[112:115]
	v_mfma_f32_16x16x32_bf16 v[100:103], v[192:195], v[216:219], v[100:103]
	v_mfma_f32_16x16x32_bf16 v[96:99], v[200:203], v[216:219], v[96:99]
	v_mfma_f32_16x16x32_bf16 v[84:87], v[192:195], v[224:227], v[84:87]
	v_mfma_f32_16x16x32_bf16 v[80:83], v[200:203], v[224:227], v[80:83]
	v_mfma_f32_16x16x32_bf16 v[68:71], v[192:195], v[232:235], v[68:71]
	v_mfma_f32_16x16x32_bf16 v[64:67], v[200:203], v[232:235], v[64:67]
	v_mfma_f32_16x16x32_bf16 v[116:119], v[196:199], v[212:215], v[116:119]
	v_mfma_f32_16x16x32_bf16 v[112:115], v[204:207], v[212:215], v[112:115]
	v_mfma_f32_16x16x32_bf16 v[100:103], v[196:199], v[220:223], v[100:103]
	v_mfma_f32_16x16x32_bf16 v[96:99], v[204:207], v[220:223], v[96:99]
	v_mfma_f32_16x16x32_bf16 v[84:87], v[196:199], v[228:231], v[84:87]
	v_mfma_f32_16x16x32_bf16 v[80:83], v[204:207], v[228:231], v[80:83]
	v_mfma_f32_16x16x32_bf16 v[68:71], v[196:199], v[236:239], v[68:71]
	v_mfma_f32_16x16x32_bf16 v[64:67], v[204:207], v[236:239], v[64:67]
	s_setprio 0
	s_barrier
; #define PG8_STAGE(bufoff, gbase, voff) do { _Pragma("unroll") for (int _i = 0; _i < 2; ++_i) \
;         __builtin_amdgcn_global_load_lds((const unsigned*)((const char*)(gbase) + (voff)[_i]), (PG8_LAS unsigned*)(lds + (bufoff) + ldsw + _i * 8192), 16, 0, 0); } while (0)
; #define PG8_LDA(dst, b, h) do { _Pragma("unroll") for (int m = 0; m < 4; ++m) _Pragma("unroll") for (int k = 0; k < 2; ++k) dst[m][k] = *(const PG8_LAS bf16x8*)(lds + PG8_SA(b, h) + aoff + m * 2048 + k * 1024); } while (0)
; #define PG8_MMA(ai, bj, At, Bt) do { __builtin_amdgcn_s_setprio(1); _Pragma("unroll") for (int m = 0; m < 4; ++m) _Pragma("unroll") for (int n = 0; n < 2; ++n) _Pragma("unroll") for (int k = 0; k < 2; ++k) \
;         acc[ai][bj][m][n] = __builtin_amdgcn_mfma_f32_16x16x32_bf16(Bt[n][k], At[m][k], acc[ai][bj][m][n], 0, 0, 0); __builtin_amdgcn_s_setprio(0); } while (0)
; #define PG8_WAIT_V(n) asm volatile("s_waitcnt vmcnt(" #n ")" ::: "memory")
; #define PG8_WAIT_L(n) asm volatile("s_waitcnt lgkmcnt(" #n ")" ::: "memory")
; #define PG8_BAR __builtin_amdgcn_s_barrier()
; #define PG8_SCHED __builtin_amdgcn_sched_barrier(0)
; template <class Epi, class Sched, bool ALIGN_EPI = false, bool SP2 = false>
; __device__ __forceinline__ void gemm_phase(PG8_LAS unsigned char* lds, const Gemm g, const Sched& S, const Epi& E, const int tid) {
;     ...
;         for (int t = 0; t < nt; t += 2) {
;     ...
;             PG8_LDA(At, 1, 1); PG8_STAGE(PG8_SB(1, 0), b3, voffB); PG8_STAGE(PG8_SB(1, 1), b3 + hstepB, voffB); PG8_STAGE(PG8_SA(1, 0), a3, voffA);
;             PG8_WAIT_V(8); PG8_WAIT_L(0); PG8_BAR; PG8_MMA(1, 0, At, B0); PG8_MMA(1, 1, At, B1); PG8_BAR; PG8_SCHED;
	s_add_i32 s22, s36, s68
	v_lshl_add_u64 v[166:167], v[166:167], 0, s[76:77]
	s_mov_b32 m0, s22
	ds_read_b128 v[208:211], v157 offset:49152
	ds_read_b128 v[212:215], v157 offset:50176
	ds_read_b128 v[216:219], v157 offset:51200
	ds_read_b128 v[220:223], v157 offset:52224
	ds_read_b128 v[224:227], v157 offset:53248
	ds_read_b128 v[228:231], v157 offset:54272
	ds_read_b128 v[232:235], v157 offset:55296
	ds_read_b128 v[236:239], v157 offset:56320
	global_load_lds_dwordx4 v[166:167], off
	s_add_i32 m0, s22, 0x2000
	s_add_u32 s18, s18, 0x40080
	v_lshl_add_u64 v[166:167], v[240:241], 0, s[76:77]
	s_addc_u32 s19, s19, 0
	s_add_i32 s22, s37, s68
	global_load_lds_dwordx4 v[166:167], off
	v_lshl_add_u64 v[166:167], s[18:19], 0, v[140:141]
	s_mov_b32 m0, s22
	s_nop 0
	global_load_lds_dwordx4 v[166:167], off
	v_lshl_add_u64 v[166:167], s[18:19], 0, v[136:137]
	s_add_i32 m0, s22, 0x2000
	s_nop 0
	global_load_lds_dwordx4 v[166:167], off
	v_lshl_add_u64 v[166:167], v[242:243], 0, s[76:77]
	s_mov_b32 m0, s84
	s_nop 0
	global_load_lds_dwordx4 v[166:167], off
	v_lshl_add_u64 v[166:167], v[244:245], 0, s[76:77]
	s_mov_b32 m0, s87
	s_nop 0
	global_load_lds_dwordx4 v[166:167], off
	s_waitcnt vmcnt(8)
	s_waitcnt lgkmcnt(0)
	s_setprio 1
	s_barrier
	v_mfma_f32_16x16x32_bf16 v[60:63], v[148:151], v[208:211], v[60:63]
	v_mfma_f32_16x16x32_bf16 v[56:59], v[162:165], v[208:211], v[56:59]
	v_mfma_f32_16x16x32_bf16 v[44:47], v[148:151], v[216:219], v[44:47]
	v_mfma_f32_16x16x32_bf16 v[40:43], v[162:165], v[216:219], v[40:43]
	v_mfma_f32_16x16x32_bf16 v[28:31], v[148:151], v[224:227], v[28:31]
	v_mfma_f32_16x16x32_bf16 v[24:27], v[162:165], v[224:227], v[24:27]
	v_mfma_f32_16x16x32_bf16 v[12:15], v[148:151], v[232:235], v[12:15]
	v_mfma_f32_16x16x32_bf16 v[8:11], v[162:165], v[232:235], v[8:11]
	v_mfma_f32_16x16x32_bf16 v[60:63], v[158:161], v[212:215], v[60:63]
	v_mfma_f32_16x16x32_bf16 v[56:59], v[188:191], v[212:215], v[56:59]
	v_mfma_f32_16x16x32_bf16 v[44:47], v[158:161], v[220:223], v[44:47]
	v_mfma_f32_16x16x32_bf16 v[40:43], v[188:191], v[220:223], v[40:43]
	v_mfma_f32_16x16x32_bf16 v[28:31], v[158:161], v[228:231], v[28:31]
	v_mfma_f32_16x16x32_bf16 v[24:27], v[188:191], v[228:231], v[24:27]
	v_mfma_f32_16x16x32_bf16 v[12:15], v[158:161], v[236:239], v[12:15]
	v_mfma_f32_16x16x32_bf16 v[8:11], v[188:191], v[236:239], v[8:11]
	s_setprio 0
	s_setprio 1
	v_mfma_f32_16x16x32_bf16 v[52:55], v[192:195], v[208:211], v[52:55]
	v_mfma_f32_16x16x32_bf16 v[48:51], v[200:203], v[208:211], v[48:51]
	v_mfma_f32_16x16x32_bf16 v[36:39], v[192:195], v[216:219], v[36:39]
	v_mfma_f32_16x16x32_bf16 v[32:35], v[200:203], v[216:219], v[32:35]
	v_mfma_f32_16x16x32_bf16 v[20:23], v[192:195], v[224:227], v[20:23]
	v_mfma_f32_16x16x32_bf16 v[16:19], v[200:203], v[224:227], v[16:19]
	v_mfma_f32_16x16x32_bf16 v[4:7], v[192:195], v[232:235], v[4:7]
	v_mfma_f32_16x16x32_bf16 v[0:3], v[200:203], v[232:235], v[0:3]
	v_mfma_f32_16x16x32_bf16 v[52:55], v[196:199], v[212:215], v[52:55]
	v_mfma_f32_16x16x32_bf16 v[48:51], v[204:207], v[212:215], v[48:51]
	v_mfma_f32_16x16x32_bf16 v[36:39], v[196:199], v[220:223], v[36:39]
	v_mfma_f32_16x16x32_bf16 v[32:35], v[204:207], v[220:223], v[32:35]
	v_mfma_f32_16x16x32_bf16 v[20:23], v[196:199], v[228:231], v[20:23]
	v_mfma_f32_16x16x32_bf16 v[16:19], v[204:207], v[228:231], v[16:19]
	v_mfma_f32_16x16x32_bf16 v[4:7], v[196:199], v[236:239], v[4:7]
	v_mfma_f32_16x16x32_bf16 v[0:3], v[204:207], v[236:239], v[0:3]
	s_setprio 0
	s_barrier
	s_add_i32 s31, s31, 2
	s_add_u32 s8, s8, 0x100
	s_addc_u32 s9, s9, 0
	s_add_u32 s29, s29, 0x100
	s_addc_u32 s30, s30, 0
	s_cmp_gt_u32 s31, 13
	s_cbranch_scc0 .LBB0_35
	s_and_b64 vcc, exec, s[10:11]
	s_cbranch_vccz .LBB0_38
	s_barrier

; #define PG8_STAGE(bufoff, gbase, voff) do { _Pragma("unroll") for (int _i = 0; _i < 2; ++_i) \
;         __builtin_amdgcn_global_load_lds((const unsigned*)((const char*)(gbase) + (voff)[_i]), (PG8_LAS unsigned*)(lds + (bufoff) + ldsw + _i * 8192), 16, 0, 0); } while (0)
; #define PG8_LDA(dst, b, h) do { _Pragma("unroll") for (int m = 0; m < 4; ++m) _Pragma("unroll") for (int k = 0; k < 2; ++k) dst[m][k] = *(const PG8_LAS bf16x8*)(lds + PG8_SA(b, h) + aoff + m * 2048 + k * 1024); } while (0)
; #define PG8_MMA(ai, bj, At, Bt) do { __builtin_amdgcn_s_setprio(1); _Pragma("unroll") for (int m = 0; m < 4; ++m) _Pragma("unroll") for (int n = 0; n < 2; ++n) _Pragma("unroll") for (int k = 0; k < 2; ++k) \
;         acc[ai][bj][m][n] = __builtin_amdgcn_mfma_f32_16x16x32_bf16(Bt[n][k], At[m][k], acc[ai][bj][m][n], 0, 0, 0); __builtin_amdgcn_s_setprio(0); } while (0)
; #define PG8_WAIT_V(n) asm volatile("s_waitcnt vmcnt(" #n ")" ::: "memory")
; #define PG8_WAIT_L(n) asm volatile("s_waitcnt lgkmcnt(" #n ")" ::: "memory")
; #define PG8_BAR __builtin_amdgcn_s_barrier()
; #define PG8_SCHED __builtin_amdgcn_sched_barrier(0)
; template <class Epi, class Sched, bool ALIGN_EPI = false, bool SP2 = false>
; __device__ __forceinline__ void gemm_phase(PG8_LAS unsigned char* lds, const Gemm g, const Sched& S, const Epi& E, const int tid) {
;     ...
;             PG8_WAIT_V(8); PG8_WAIT_L(0); PG8_BAR; PG8_MMA(0, 0, At, B0); PG8_MMA(0, 1, At, B1); PG8_BAR; PG8_SCHED;
;             PG8_LDA(At, 0, 1); PG8_STAGE(PG8_SB(0, 0), b2, voffB); PG8_STAGE(PG8_SB(0, 1), b2 + hstepB, voffB); PG8_STAGE(PG8_SA(0, 0), a2, voffA);
;             PG8_WAIT_V(8); PG8_WAIT_L(0); PG8_BAR; PG8_MMA(1, 0, At, B0); PG8_MMA(1, 1, At, B1); PG8_BAR; PG8_SCHED;
.Lkw_pl_0:
	s_waitcnt lgkmcnt(0)
	s_setprio 1
	s_barrier
	v_mfma_f32_16x16x32_bf16 v[124:127], v[148:151], v[208:211], v[124:127]
	v_mfma_f32_16x16x32_bf16 v[120:123], v[162:165], v[208:211], v[120:123]
	v_mfma_f32_16x16x32_bf16 v[108:111], v[148:151], v[216:219], v[108:111]
	v_mfma_f32_16x16x32_bf16 v[104:107], v[162:165], v[216:219], v[104:107]
	v_mfma_f32_16x16x32_bf16 v[92:95], v[148:151], v[224:227], v[92:95]
	v_mfma_f32_16x16x32_bf16 v[88:91], v[162:165], v[224:227], v[88:91]
	v_mfma_f32_16x16x32_bf16 v[76:79], v[148:151], v[232:235], v[76:79]
	v_mfma_f32_16x16x32_bf16 v[72:75], v[162:165], v[232:235], v[72:75]
	v_mfma_f32_16x16x32_bf16 v[124:127], v[158:161], v[212:215], v[124:127]
	v_mfma_f32_16x16x32_bf16 v[120:123], v[188:191], v[212:215], v[120:123]
	v_mfma_f32_16x16x32_bf16 v[108:111], v[158:161], v[220:223], v[108:111]
	v_mfma_f32_16x16x32_bf16 v[104:107], v[188:191], v[220:223], v[104:107]
	v_mfma_f32_16x16x32_bf16 v[92:95], v[158:161], v[228:231], v[92:95]
	v_mfma_f32_16x16x32_bf16 v[88:91], v[188:191], v[228:231], v[88:91]
	v_mfma_f32_16x16x32_bf16 v[76:79], v[158:161], v[236:239], v[76:79]
	v_mfma_f32_16x16x32_bf16 v[72:75], v[188:191], v[236:239], v[72:75]
	s_setprio 0
	s_setprio 1
	v_mfma_f32_16x16x32_bf16 v[116:119], v[192:195], v[208:211], v[116:119]
	v_mfma_f32_16x16x32_bf16 v[112:115], v[200:203], v[208:211], v[112:115]
	v_mfma_f32_16x16x32_bf16 v[100:103], v[192:195], v[216:219], v[100:103]
	v_mfma_f32_16x16x32_bf16 v[96:99], v[200:203], v[216:219], v[96:99]
	v_mfma_f32_16x16x32_bf16 v[84:87], v[192:195], v[224:227], v[84:87]
	v_mfma_f32_16x16x32_bf16 v[80:83], v[200:203], v[224:227], v[80:83]
	v_mfma_f32_16x16x32_bf16 v[68:71], v[192:195], v[232:235], v[68:71]
	v_mfma_f32_16x16x32_bf16 v[64:67], v[200:203], v[232:235], v[64:67]
	v_mfma_f32_16x16x32_bf16 v[116:119], v[196:199], v[212:215], v[116:119]
	v_mfma_f32_16x16x32_bf16 v[112:115], v[204:207], v[212:215], v[112:115]
	v_mfma_f32_16x16x32_bf16 v[100:103], v[196:199], v[220:223], v[100:103]
	v_mfma_f32_16x16x32_bf16 v[96:99], v[204:207], v[220:223], v[96:99]
	v_mfma_f32_16x16x32_bf16 v[84:87], v[196:199], v[228:231], v[84:87]
	v_mfma_f32_16x16x32_bf16 v[80:83], v[204:207], v[228:231], v[80:83]
	v_mfma_f32_16x16x32_bf16 v[68:71], v[196:199], v[236:239], v[68:71]
	v_mfma_f32_16x16x32_bf16 v[64:67], v[204:207], v[236:239], v[64:67]
	s_setprio 0
	s_barrier
	s_add_i32 s50, s50, s81
	v_lshl_add_u64 v[166:167], s[48:49], 0, v[138:139]
	s_mov_b32 m0, s50
	ds_read_b128 v[208:211], v157 offset:16384
	ds_read_b128 v[212:215], v157 offset:17408
	ds_read_b128 v[216:219], v157 offset:18432
	ds_read_b128 v[220:223], v157 offset:19456
	ds_read_b128 v[224:227], v157 offset:20480
	ds_read_b128 v[228:231], v157 offset:21504
	ds_read_b128 v[232:235], v157 offset:22528
	ds_read_b128 v[236:239], v157 offset:23552
	global_load_lds_dwordx4 v[166:167], off
	s_add_i32 m0, s50, 0x2000
	v_lshl_add_u64 v[240:241], s[48:49], 0, v[142:143]
	s_add_u32 s48, s48, s21
	s_addc_u32 s49, s49, 0
	s_add_i32 s46, s46, s81
	global_load_lds_dwordx4 v[240:241], off
	v_lshl_add_u64 v[242:243], s[48:49], 0, v[138:139]
	s_mov_b32 m0, s46
	v_lshl_add_u64 v[244:245], s[48:49], 0, v[142:143]
	global_load_lds_dwordx4 v[242:243], off
	s_add_i32 m0, s46, 0x2000
	v_lshl_add_u64 v[246:247], s[92:93], 0, v[136:137]
	global_load_lds_dwordx4 v[244:245], off
	s_mov_b32 m0, s72
	v_lshl_add_u64 v[248:249], s[92:93], 0, v[140:141]
	global_load_lds_dwordx4 v[246:247], off
	s_mov_b32 m0, s73
	s_nop 0
	global_load_lds_dwordx4 v[248:249], off
	s_cmp_eq_u32 s99, 1
	s_cbranch_scc1 .Lkw_pl_1
	s_waitcnt vmcnt(8)
.Lkw_pl_1:
	s_waitcnt lgkmcnt(0)
	s_setprio 1
	s_barrier
	v_mfma_f32_16x16x32_bf16 v[60:63], v[148:151], v[208:211], v[60:63]
	v_mfma_f32_16x16x32_bf16 v[56:59], v[162:165], v[208:211], v[56:59]
	v_mfma_f32_16x16x32_bf16 v[44:47], v[148:151], v[216:219], v[44:47]
	v_mfma_f32_16x16x32_bf16 v[40:43], v[162:165], v[216:219], v[40:43]
	v_mfma_f32_16x16x32_bf16 v[28:31], v[148:151], v[224:227], v[28:31]
	v_mfma_f32_16x16x32_bf16 v[24:27], v[162:165], v[224:227], v[24:27]
	v_mfma_f32_16x16x32_bf16 v[12:15], v[148:151], v[232:235], v[12:15]
	v_mfma_f32_16x16x32_bf16 v[8:11], v[162:165], v[232:235], v[8:11]
	v_mfma_f32_16x16x32_bf16 v[60:63], v[158:161], v[212:215], v[60:63]
	v_mfma_f32_16x16x32_bf16 v[56:59], v[188:191], v[212:215], v[56:59]
	v_mfma_f32_16x16x32_bf16 v[44:47], v[158:161], v[220:223], v[44:47]
	v_mfma_f32_16x16x32_bf16 v[40:43], v[188:191], v[220:223], v[40:43]
	v_mfma_f32_16x16x32_bf16 v[28:31], v[158:161], v[228:231], v[28:31]
	v_mfma_f32_16x16x32_bf16 v[24:27], v[188:191], v[228:231], v[24:27]
	v_mfma_f32_16x16x32_bf16 v[12:15], v[158:161], v[236:239], v[12:15]
	v_mfma_f32_16x16x32_bf16 v[8:11], v[188:191], v[236:239], v[8:11]
	s_setprio 0
	s_setprio 1
	v_mfma_f32_16x16x32_bf16 v[52:55], v[192:195], v[208:211], v[52:55]
	v_mfma_f32_16x16x32_bf16 v[48:51], v[200:203], v[208:211], v[48:51]
	v_mfma_f32_16x16x32_bf16 v[36:39], v[192:195], v[216:219], v[36:39]
	v_mfma_f32_16x16x32_bf16 v[32:35], v[200:203], v[216:219], v[32:35]
	v_mfma_f32_16x16x32_bf16 v[20:23], v[192:195], v[224:227], v[20:23]
	v_mfma_f32_16x16x32_bf16 v[16:19], v[200:203], v[224:227], v[16:19]
	v_mfma_f32_16x16x32_bf16 v[4:7], v[192:195], v[232:235], v[4:7]
	v_mfma_f32_16x16x32_bf16 v[0:3], v[200:203], v[232:235], v[0:3]
	v_mfma_f32_16x16x32_bf16 v[52:55], v[196:199], v[212:215], v[52:55]
	v_mfma_f32_16x16x32_bf16 v[48:51], v[204:207], v[212:215], v[48:51]
	v_mfma_f32_16x16x32_bf16 v[36:39], v[196:199], v[220:223], v[36:39]
	v_mfma_f32_16x16x32_bf16 v[32:35], v[204:207], v[220:223], v[32:35]
	v_mfma_f32_16x16x32_bf16 v[20:23], v[196:199], v[228:231], v[20:23]
	v_mfma_f32_16x16x32_bf16 v[16:19], v[204:207], v[228:231], v[16:19]
	v_mfma_f32_16x16x32_bf16 v[4:7], v[196:199], v[236:239], v[4:7]
	v_mfma_f32_16x16x32_bf16 v[0:3], v[204:207], v[236:239], v[0:3]
	s_setprio 0
	s_barrier
; #define PG8_STAGE(bufoff, gbase, voff) do { _Pragma("unroll") for (int _i = 0; _i < 2; ++_i) \
;         __builtin_amdgcn_global_load_lds((const unsigned*)((const char*)(gbase) + (voff)[_i]), (PG8_LAS unsigned*)(lds + (bufoff) + ldsw + _i * 8192), 16, 0, 0); } while (0)
; #define PG8_LDA(dst, b, h) do { _Pragma("unroll") for (int m = 0; m < 4; ++m) _Pragma("unroll") for (int k = 0; k < 2; ++k) dst[m][k] = *(const PG8_LAS bf16x8*)(lds + PG8_SA(b, h) + aoff + m * 2048 + k * 1024); } while (0)
; #define PG8_LDB(dst, b, h) do { _Pragma("unroll") for (int n = 0; n < 2; ++n) _Pragma("unroll") for (int k = 0; k < 2; ++k) dst[n][k] = *(const PG8_LAS bf16x8*)(lds + PG8_SB(b, h) + boff + n * 2048 + k * 1024); } while (0)
; #define PG8_MMA(ai, bj, At, Bt) do { __builtin_amdgcn_s_setprio(1); _Pragma("unroll") for (int m = 0; m < 4; ++m) _Pragma("unroll") for (int n = 0; n < 2; ++n) _Pragma("unroll") for (int k = 0; k < 2; ++k) \
;         acc[ai][bj][m][n] = __builtin_amdgcn_mfma_f32_16x16x32_bf16(Bt[n][k], At[m][k], acc[ai][bj][m][n], 0, 0, 0); __builtin_amdgcn_s_setprio(0); } while (0)
; #define PG8_WAIT_V(n) asm volatile("s_waitcnt vmcnt(" #n ")" ::: "memory")
; #define PG8_WAIT_L(n) asm volatile("s_waitcnt lgkmcnt(" #n ")" ::: "memory")
; #define PG8_BAR __builtin_amdgcn_s_barrier()
; #define PG8_SCHED __builtin_amdgcn_sched_barrier(0)
; template <class Epi, class Sched, bool ALIGN_EPI = false, bool SP2 = false>
; __device__ __forceinline__ void gemm_phase(PG8_LAS unsigned char* lds, const Gemm g, const Sched& S, const Epi& E, const int tid) {
;     ...
;             PG8_LDB(B0, 1, 0); PG8_LDB(B1, 1, 1); PG8_SCHED; PG8_LDA(At, 1, 0); PG8_STAGE(PG8_SA(0, 1), a2 + hstepA, voffA);
;             PG8_WAIT_V(8); PG8_WAIT_L(0); PG8_BAR; PG8_MMA(0, 0, At, B0); PG8_MMA(0, 1, At, B1); PG8_BAR; PG8_SCHED;
	s_add_i32 s46, 0, 0x18000
	v_add_u32_e32 v128, s46, v155
	s_add_i32 s50, 0, 0x1c000
	ds_read_b128 v[148:151], v128
	ds_read_b128 v[158:161], v128 offset:1024
	ds_read_b128 v[162:165], v128 offset:2048
	ds_read_b128 v[188:191], v128 offset:3072
	v_add_u32_e32 v128, s50, v155
	ds_read_b128 v[192:195], v128
	ds_read_b128 v[196:199], v128 offset:1024
	ds_read_b128 v[200:203], v128 offset:2048
	ds_read_b128 v[204:207], v128 offset:3072
	s_add_u32 s48, s92, s84
	s_addc_u32 s49, s93, 0
	s_mov_b32 m0, s24
	v_lshl_add_u64 v[250:251], s[48:49], 0, v[136:137]
	ds_read_b128 v[208:211], v157 offset:32768
	ds_read_b128 v[212:215], v157 offset:33792
	ds_read_b128 v[216:219], v157 offset:34816
	ds_read_b128 v[220:223], v157 offset:35840
	ds_read_b128 v[224:227], v157 offset:36864
	ds_read_b128 v[228:231], v157 offset:37888
	ds_read_b128 v[232:235], v157 offset:38912
	ds_read_b128 v[236:239], v157 offset:39936
	global_load_lds_dwordx4 v[250:251], off
	v_lshl_add_u64 v[250:251], s[48:49], 0, v[140:141]
	s_mov_b32 m0, s25
	s_nop 0
	global_load_lds_dwordx4 v[250:251], off
	s_waitcnt vmcnt(8)
	s_waitcnt lgkmcnt(0)
	s_setprio 1
	s_barrier
	v_mfma_f32_16x16x32_bf16 v[124:127], v[148:151], v[208:211], v[124:127]
	v_mfma_f32_16x16x32_bf16 v[120:123], v[162:165], v[208:211], v[120:123]
	v_mfma_f32_16x16x32_bf16 v[108:111], v[148:151], v[216:219], v[108:111]
	v_mfma_f32_16x16x32_bf16 v[104:107], v[162:165], v[216:219], v[104:107]
	v_mfma_f32_16x16x32_bf16 v[92:95], v[148:151], v[224:227], v[92:95]
	v_mfma_f32_16x16x32_bf16 v[88:91], v[162:165], v[224:227], v[88:91]
	v_mfma_f32_16x16x32_bf16 v[76:79], v[148:151], v[232:235], v[76:79]
	v_mfma_f32_16x16x32_bf16 v[72:75], v[162:165], v[232:235], v[72:75]
	v_mfma_f32_16x16x32_bf16 v[124:127], v[158:161], v[212:215], v[124:127]
	v_mfma_f32_16x16x32_bf16 v[120:123], v[188:191], v[212:215], v[120:123]
	v_mfma_f32_16x16x32_bf16 v[108:111], v[158:161], v[220:223], v[108:111]
	v_mfma_f32_16x16x32_bf16 v[104:107], v[188:191], v[220:223], v[104:107]
	v_mfma_f32_16x16x32_bf16 v[92:95], v[158:161], v[228:231], v[92:95]
	v_mfma_f32_16x16x32_bf16 v[88:91], v[188:191], v[228:231], v[88:91]
	v_mfma_f32_16x16x32_bf16 v[76:79], v[158:161], v[236:239], v[76:79]
	v_mfma_f32_16x16x32_bf16 v[72:75], v[188:191], v[236:239], v[72:75]
	s_setprio 0
	s_setprio 1
	v_mfma_f32_16x16x32_bf16 v[116:119], v[192:195], v[208:211], v[116:119]
	v_mfma_f32_16x16x32_bf16 v[112:115], v[200:203], v[208:211], v[112:115]
	v_mfma_f32_16x16x32_bf16 v[100:103], v[192:195], v[216:219], v[100:103]
	v_mfma_f32_16x16x32_bf16 v[96:99], v[200:203], v[216:219], v[96:99]
	v_mfma_f32_16x16x32_bf16 v[84:87], v[192:195], v[224:227], v[84:87]
	v_mfma_f32_16x16x32_bf16 v[80:83], v[200:203], v[224:227], v[80:83]
	v_mfma_f32_16x16x32_bf16 v[68:71], v[192:195], v[232:235], v[68:71]
	v_mfma_f32_16x16x32_bf16 v[64:67], v[200:203], v[232:235], v[64:67]
	v_mfma_f32_16x16x32_bf16 v[116:119], v[196:199], v[212:215], v[116:119]
	v_mfma_f32_16x16x32_bf16 v[112:115], v[204:207], v[212:215], v[112:115]
	v_mfma_f32_16x16x32_bf16 v[100:103], v[196:199], v[220:223], v[100:103]
	v_mfma_f32_16x16x32_bf16 v[96:99], v[204:207], v[220:223], v[96:99]
	v_mfma_f32_16x16x32_bf16 v[84:87], v[196:199], v[228:231], v[84:87]
	v_mfma_f32_16x16x32_bf16 v[80:83], v[204:207], v[228:231], v[80:83]
	v_mfma_f32_16x16x32_bf16 v[68:71], v[196:199], v[236:239], v[68:71]
	v_mfma_f32_16x16x32_bf16 v[64:67], v[204:207], v[236:239], v[64:67]
	s_setprio 0
	s_barrier
; #define PG8_STAGE(bufoff, gbase, voff) do { _Pragma("unroll") for (int _i = 0; _i < 2; ++_i) \
;         __builtin_amdgcn_global_load_lds((const unsigned*)((const char*)(gbase) + (voff)[_i]), (PG8_LAS unsigned*)(lds + (bufoff) + ldsw + _i * 8192), 16, 0, 0); } while (0)
; #define PG8_LDA(dst, b, h) do { _Pragma("unroll") for (int m = 0; m < 4; ++m) _Pragma("unroll") for (int k = 0; k < 2; ++k) dst[m][k] = *(const PG8_LAS bf16x8*)(lds + PG8_SA(b, h) + aoff + m * 2048 + k * 1024); } while (0)
; #define PG8_MMA(ai, bj, At, Bt) do { __builtin_amdgcn_s_setprio(1); _Pragma("unroll") for (int m = 0; m < 4; ++m) _Pragma("unroll") for (int n = 0; n < 2; ++n) _Pragma("unroll") for (int k = 0; k < 2; ++k) \
;         acc[ai][bj][m][n] = __builtin_amdgcn_mfma_f32_16x16x32_bf16(Bt[n][k], At[m][k], acc[ai][bj][m][n], 0, 0, 0); __builtin_amdgcn_s_setprio(0); } while (0)
; #define PG8_WAIT_V(n) asm volatile("s_waitcnt vmcnt(" #n ")" ::: "memory")
; #define PG8_WAIT_L(n) asm volatile("s_waitcnt lgkmcnt(" #n ")" ::: "memory")
; #define PG8_BAR __builtin_amdgcn_s_barrier()
; #define PG8_SCHED __builtin_amdgcn_sched_barrier(0)
; template <class Epi, class Sched, bool ALIGN_EPI = false, bool SP2 = false>
; __device__ __forceinline__ void gemm_phase(PG8_LAS unsigned char* lds, const Gemm g, const Sched& S, const Epi& E, const int tid) {
;     ...
;         for (int t = 0; t < nt; t += 2) {
;     ...
;             PG8_LDA(At, 1, 1); PG8_STAGE(PG8_SB(1, 0), b3, voffB); PG8_STAGE(PG8_SB(1, 1), b3 + hstepB, voffB); PG8_STAGE(PG8_SA(1, 0), a3, voffA);
;             PG8_WAIT_V(8); PG8_WAIT_L(0); PG8_BAR; PG8_MMA(1, 0, At, B0); PG8_MMA(1, 1, At, B1); PG8_BAR; PG8_SCHED;
	s_add_i32 s46, s46, s81
	v_lshl_add_u64 v[166:167], v[166:167], 0, s[76:77]
	s_mov_b32 m0, s46
	ds_read_b128 v[208:211], v157 offset:49152
	ds_read_b128 v[212:215], v157 offset:50176
	ds_read_b128 v[216:219], v157 offset:51200
	ds_read_b128 v[220:223], v157 offset:52224
	ds_read_b128 v[224:227], v157 offset:53248
	ds_read_b128 v[228:231], v157 offset:54272
	ds_read_b128 v[232:235], v157 offset:55296
	ds_read_b128 v[236:239], v157 offset:56320
	global_load_lds_dwordx4 v[166:167], off
	v_lshl_add_u64 v[166:167], v[240:241], 0, s[76:77]
	s_add_i32 m0, s46, 0x2000
	s_add_i32 s46, s50, s81
	global_load_lds_dwordx4 v[166:167], off
	v_lshl_add_u64 v[166:167], v[242:243], 0, s[76:77]
	s_mov_b32 m0, s46
	s_nop 0
	global_load_lds_dwordx4 v[166:167], off
	v_lshl_add_u64 v[166:167], v[244:245], 0, s[76:77]
	s_add_i32 m0, s46, 0x2000
	s_nop 0
	global_load_lds_dwordx4 v[166:167], off
	v_lshl_add_u64 v[166:167], v[246:247], 0, s[76:77]
	s_mov_b32 m0, s27
	s_nop 0
	global_load_lds_dwordx4 v[166:167], off
	v_lshl_add_u64 v[166:167], v[248:249], 0, s[76:77]
	s_mov_b32 m0, s28
	s_nop 0
	global_load_lds_dwordx4 v[166:167], off
	s_waitcnt vmcnt(8)
	s_waitcnt lgkmcnt(0)
	s_setprio 1
	s_barrier
	v_mfma_f32_16x16x32_bf16 v[60:63], v[148:151], v[208:211], v[60:63]
	v_mfma_f32_16x16x32_bf16 v[56:59], v[162:165], v[208:211], v[56:59]
	v_mfma_f32_16x16x32_bf16 v[44:47], v[148:151], v[216:219], v[44:47]
	v_mfma_f32_16x16x32_bf16 v[40:43], v[162:165], v[216:219], v[40:43]
	v_mfma_f32_16x16x32_bf16 v[28:31], v[148:151], v[224:227], v[28:31]
	v_mfma_f32_16x16x32_bf16 v[24:27], v[162:165], v[224:227], v[24:27]
	v_mfma_f32_16x16x32_bf16 v[12:15], v[148:151], v[232:235], v[12:15]
	v_mfma_f32_16x16x32_bf16 v[8:11], v[162:165], v[232:235], v[8:11]
	v_mfma_f32_16x16x32_bf16 v[60:63], v[158:161], v[212:215], v[60:63]
	v_mfma_f32_16x16x32_bf16 v[56:59], v[188:191], v[212:215], v[56:59]
	v_mfma_f32_16x16x32_bf16 v[44:47], v[158:161], v[220:223], v[44:47]
	v_mfma_f32_16x16x32_bf16 v[40:43], v[188:191], v[220:223], v[40:43]
	v_mfma_f32_16x16x32_bf16 v[28:31], v[158:161], v[228:231], v[28:31]
	v_mfma_f32_16x16x32_bf16 v[24:27], v[188:191], v[228:231], v[24:27]
	v_mfma_f32_16x16x32_bf16 v[12:15], v[158:161], v[236:239], v[12:15]
	v_mfma_f32_16x16x32_bf16 v[8:11], v[188:191], v[236:239], v[8:11]
	s_setprio 0
	s_setprio 1
	v_mfma_f32_16x16x32_bf16 v[52:55], v[192:195], v[208:211], v[52:55]
	v_mfma_f32_16x16x32_bf16 v[48:51], v[200:203], v[208:211], v[48:51]
	v_mfma_f32_16x16x32_bf16 v[36:39], v[192:195], v[216:219], v[36:39]
	v_mfma_f32_16x16x32_bf16 v[32:35], v[200:203], v[216:219], v[32:35]
	v_mfma_f32_16x16x32_bf16 v[20:23], v[192:195], v[224:227], v[20:23]
	v_mfma_f32_16x16x32_bf16 v[16:19], v[200:203], v[224:227], v[16:19]
	v_mfma_f32_16x16x32_bf16 v[4:7], v[192:195], v[232:235], v[4:7]
	v_mfma_f32_16x16x32_bf16 v[0:3], v[200:203], v[232:235], v[0:3]
	v_mfma_f32_16x16x32_bf16 v[52:55], v[196:199], v[212:215], v[52:55]
	v_mfma_f32_16x16x32_bf16 v[48:51], v[204:207], v[212:215], v[48:51]
	v_mfma_f32_16x16x32_bf16 v[36:39], v[196:199], v[220:223], v[36:39]
	v_mfma_f32_16x16x32_bf16 v[32:35], v[204:207], v[220:223], v[32:35]
	v_mfma_f32_16x16x32_bf16 v[20:23], v[196:199], v[228:231], v[20:23]
	v_mfma_f32_16x16x32_bf16 v[16:19], v[204:207], v[228:231], v[16:19]
	v_mfma_f32_16x16x32_bf16 v[4:7], v[196:199], v[236:239], v[4:7]
	v_mfma_f32_16x16x32_bf16 v[0:3], v[204:207], v[236:239], v[0:3]
	s_setprio 0
	s_barrier
	s_add_u32 s8, s8, 0x100
	s_addc_u32 s9, s9, 0
	s_add_u32 s44, s44, 0x100
	s_addc_u32 s45, s45, 0
	s_cmp_ge_u32 s47, s14
	s_mov_b32 s46, s47
	s_cbranch_scc0 .LBB0_468
	s_and_b64 vcc, exec, s[22:23]
	s_cbranch_vccz .LBB0_471
	s_barrier
